# MoBA prologue de-serialisation: diagonal K/V block loads issued before the gating loop into spare registers (7 VGPR quads + a[0:3]), on top of q7 order
# baseline (speedup 1.0000x reference)
; __device__ __forceinline__ void moba_unit(const Ctx& C, int unit, const float* KM) {
;     ...
;         const float* TC = (const float*)(C.ws + WS_TABC) + h * 4096;
;         float tv[8], kv[2]; v4u qv[8];
; #pragma unroll
;         for (int i = 0; i < 8; ++i) { const int d = tid + 512 * i; tv[i] = (d < ndist) ? TC[d] : 0.f; }
; #pragma unroll
;         for (int i = 0; i < 2; ++i) { const int e = tid + 512 * i; kv[i] = (e < qb * 64) ? KM[(size_t)(b * 16 + (e >> 6)) * 512 + h * 64 + (e & 63)] : 0.f; }
;         { const bf16* qp = Zb + (size_t)(qb * 256 + (tid & 255)) * ZC + QC + h * 64;
; #pragma unroll
;             for (int c = 0; c < 8; ++c) qv[c] = *(const v4u*)(qp + 8 * c); }
.LBB0_402:
	s_or_b64 exec, exec, s[66:67]
	s_lshl_b32 s22, s20, 6
	s_mul_i32 s20, s71, 0x2600000
	s_add_u32 s20, s64, s20
	s_addc_u32 s21, s65, 0
	s_add_u32 s66, s20, 0xbc00000
	s_addc_u32 s67, s21, 0
	v_and_b32_e32 v33, 0xff, v132
	v_or_b32_e32 v2, s75, v33
	v_mov_b64_e32 v[0:1], s[66:67]
	v_mad_u64_u32 v[0:1], s[20:21], v2, s33, v[0:1]
	s_lshl_b32 s36, s22, 1
	v_lshl_add_u64 v[0:1], v[0:1], 0, s[36:37]
	v_lshl_add_u64 v[12:13], v[0:1], 0, s[88:89]
	v_add_co_u32_e32 v0, vcc, 0x1000, v0
	v_lshl_add_u32 v46, v132, 2, 0
	s_nop 0
	v_addc_co_u32_e32 v1, vcc, 0, v1, vcc
	global_load_dwordx4 v[20:23], v[12:13], off offset:32
	global_load_dwordx4 v[24:27], v[12:13], off offset:16
	global_load_dwordx4 v[28:31], v[0:1], off offset:2560
	s_nop 0
	global_load_dwordx4 v[0:3], v[12:13], off offset:112
	global_load_dwordx4 v[4:7], v[12:13], off offset:96
	global_load_dwordx4 v[8:11], v[12:13], off offset:80
	global_load_dwordx4 v[16:19], v[12:13], off offset:48
	s_nop 0
	global_load_dwordx4 v[12:15], v[12:13], off offset:64
	s_add_u32 s100, s66, s36
	s_addc_u32 s101, s67, 0
	v_lshlrev_b32_e32 v226, 4, v132
	v_and_b32_e32 v226, 0x70, v226
	v_mov_b32_e32 v227, 0
	v_ashrrev_i32_e32 v188, 3, v132
	v_lshl_add_u64 v[104:105], s[100:101], 0, v[226:227]
	v_add_u32_e32 v170, s75, v188
	v_mad_i64_i32 v[170:171], s[100:101], v170, s33, v[104:105]
	v_add_co_u32_e32 v172, vcc, 0x1000, v170
	s_nop 1
	v_addc_co_u32_e32 v173, vcc, 0, v171, vcc
	v_add_co_u32_e32 v174, vcc, s5, v170
	s_nop 1
	v_addc_co_u32_e32 v175, vcc, 0, v171, vcc
	global_load_dwordx4 v[170:173], v[172:173], off offset:3584
	global_load_dwordx4 v[174:177], v[174:175], off offset:512
	v_add_u32_e32 v189, 64, v188
	v_add_u32_e32 v178, s75, v189
	v_mad_i64_i32 v[178:179], s[100:101], v178, s33, v[104:105]
	v_add_co_u32_e32 v180, vcc, 0x1000, v178
	s_nop 1
	v_addc_co_u32_e32 v181, vcc, 0, v179, vcc
	v_add_co_u32_e32 v182, vcc, s5, v178
	s_nop 1
	v_addc_co_u32_e32 v183, vcc, 0, v179, vcc
	global_load_dwordx4 v[178:181], v[180:181], off offset:3584
	global_load_dwordx4 v[182:185], v[182:183], off offset:512
	v_add_u32_e32 v190, 0x80, v188
	v_add_u32_e32 v222, s75, v190
	v_mad_i64_i32 v[222:223], s[100:101], v222, s33, v[104:105]
	v_add_co_u32_e32 v224, vcc, 0x1000, v222
	s_nop 1
	v_addc_co_u32_e32 v225, vcc, 0, v223, vcc
	v_add_co_u32_e32 v238, vcc, s5, v222
	s_nop 1
	v_addc_co_u32_e32 v239, vcc, 0, v223, vcc
	global_load_dwordx4 v[222:225], v[224:225], off offset:3584
	global_load_dwordx4 v[238:241], v[238:239], off offset:512
	v_add_u32_e32 v191, 0xc0, v188
	v_add_u32_e32 v242, s75, v191
	v_mad_i64_i32 v[242:243], s[100:101], v242, s33, v[104:105]
	v_add_co_u32_e32 v244, vcc, 0x1000, v242
	s_nop 1
	v_addc_co_u32_e32 v245, vcc, 0, v243, vcc
	v_add_co_u32_e32 v226, vcc, s5, v242
	s_nop 1
	v_addc_co_u32_e32 v227, vcc, 0, v243, vcc
	global_load_dwordx4 v[242:245], v[244:245], off offset:3584
	global_load_dwordx4 a[0:3], v[226:227], off offset:512
	s_and_saveexec_b64 s[68:69], s[38:39]
	s_cbranch_execz .LBB0_423
	s_waitcnt vmcnt(16)
	ds_write_b32 v46, v37 offset:8192
	s_or_b64 exec, exec, s[68:69]
	s_and_saveexec_b64 s[38:39], s[40:41]
	s_cbranch_execnz .LBB0_424

; __device__ __forceinline__ void moba_unit(const Ctx& C, int unit, const float* KM) {
;     ...
;         for (int i = 0; i < 8; ++i) { const int d = tid + 512 * i; if (d < ndist) tabC[d] = tv[i]; }
; #pragma unroll
;         for (int i = 0; i < 2; ++i) { const int e = tid + 512 * i; if (e < qb * 64) kml[e] = kv[i] * (1.0f / 256.0f); }
.LBB0_405:
	s_waitcnt vmcnt(16)
	ds_write_b32 v46, v38 offset:12288
	s_or_b64 exec, exec, s[38:39]
	s_and_saveexec_b64 s[38:39], s[44:45]
	s_cbranch_execnz .LBB0_426

; __device__ __forceinline__ void moba_unit(const Ctx& C, int unit, const float* KM) {
;     ...
;         for (int i = 0; i < 8; ++i) { const int d = tid + 512 * i; if (d < ndist) tabC[d] = tv[i]; }
; #pragma unroll
;         for (int i = 0; i < 2; ++i) { const int e = tid + 512 * i; if (e < qb * 64) kml[e] = kv[i] * (1.0f / 256.0f); }
.LBB0_407:
	s_waitcnt vmcnt(16)
	ds_write_b32 v46, v40 offset:16384
	s_or_b64 exec, exec, s[38:39]
	s_and_saveexec_b64 s[38:39], s[48:49]
	s_cbranch_execnz .LBB0_428

; __device__ __forceinline__ void moba_unit(const Ctx& C, int unit, const float* KM) {
;     ...
;         for (int i = 0; i < 8; ++i) { const int d = tid + 512 * i; if (d < ndist) tabC[d] = tv[i]; }
; #pragma unroll
;         for (int i = 0; i < 2; ++i) { const int e = tid + 512 * i; if (e < qb * 64) kml[e] = kv[i] * (1.0f / 256.0f); }
.LBB0_409:
	s_waitcnt vmcnt(16)
	ds_write_b32 v46, v43 offset:20480
	s_or_b64 exec, exec, s[38:39]
	s_and_saveexec_b64 s[38:39], s[52:53]
	s_cbranch_execnz .LBB0_430

; __device__ __forceinline__ void moba_unit(const Ctx& C, int unit, const float* KM) {
;     ...
;         for (int i = 0; i < 8; ++i) { const int d = tid + 512 * i; if (d < ndist) tabC[d] = tv[i]; }
; #pragma unroll
;         for (int i = 0; i < 2; ++i) { const int e = tid + 512 * i; if (e < qb * 64) kml[e] = kv[i] * (1.0f / 256.0f); }
.LBB0_411:
	s_waitcnt vmcnt(16)
	v_add_u32_e32 v35, 0x16000, v46
	v_mul_f32_e32 v45, 0x3b800000, v45
	ds_write_b32 v35, v45
	s_or_b64 exec, exec, s[38:39]
	s_and_saveexec_b64 s[38:39], s[56:57]
	s_cbranch_execnz .LBB0_432

; __device__ __forceinline__ float bflo(unsigned w) { return __uint_as_float(w << 16); }
; __device__ __forceinline__ float bfhi(unsigned w) { return __uint_as_float(w & 0xffff0000u); }
; __device__ __forceinline__ void moba_unit(const Ctx& C, int unit, const float* KM) {
;     ...
;         if (tid < 16) cnt[tid] = 0;
;         __syncthreads();
;         {
;         const int qsel = tid & 255, half = tid >> 8;
;         float qf[64];
; #pragma unroll
;         for (int c = 0; c < 8; ++c) { const v4u w = qv[c];
;             qf[8 * c + 0] = bflo(w.x); qf[8 * c + 1] = bfhi(w.x); qf[8 * c + 2] = bflo(w.y); qf[8 * c + 3] = bfhi(w.y);
;             qf[8 * c + 4] = bflo(w.z); qf[8 * c + 5] = bfhi(w.z); qf[8 * c + 6] = bflo(w.w); qf[8 * c + 7] = bfhi(w.w); }
;         float v1 = -3e38f, v2 = -3e38f, v3 = -3e38f; int i1 = -1, i2 = -1, i3 = -1;
.LBB0_414:
	s_or_b64 exec, exec, s[38:39]
	s_waitcnt vmcnt(16)
	v_ashrrev_i32_e32 v35, 8, v132
	v_cmp_gt_i32_e32 vcc, s70, v35
	v_mov_b32_e32 v41, 0xff61b1e6
	v_mov_b32_e32 v36, -1
	v_mov_b32_e32 v39, -1
	v_mov_b32_e32 v40, 0xff61b1e6
	v_mov_b32_e32 v38, 0xff61b1e6
	v_mov_b32_e32 v37, -1
	s_waitcnt lgkmcnt(0)
	s_barrier
	s_and_saveexec_b64 s[38:39], vcc
	s_cbranch_execz .LBB0_434
	s_waitcnt vmcnt(13)
	v_lshlrev_b32_e32 v43, 16, v28
	v_and_b32_e32 v28, 0xffff0000, v28
	v_lshlrev_b32_e32 v44, 16, v29
	v_and_b32_e32 v29, 0xffff0000, v29
	v_lshlrev_b32_e32 v45, 16, v30
	v_and_b32_e32 v30, 0xffff0000, v30
	v_lshlrev_b32_e32 v46, 16, v31
	v_and_b32_e32 v31, 0xffff0000, v31
	v_lshlrev_b32_e32 v47, 16, v24
	v_and_b32_e32 v24, 0xffff0000, v24
	v_lshlrev_b32_e32 v48, 16, v25
	v_and_b32_e32 v25, 0xffff0000, v25
	v_lshlrev_b32_e32 v49, 16, v26
	v_and_b32_e32 v26, 0xffff0000, v26
	v_lshlrev_b32_e32 v50, 16, v27
	v_and_b32_e32 v27, 0xffff0000, v27
	v_lshlrev_b32_e32 v51, 16, v20
	v_and_b32_e32 v20, 0xffff0000, v20
	v_lshlrev_b32_e32 v52, 16, v21
	v_and_b32_e32 v21, 0xffff0000, v21
	v_lshlrev_b32_e32 v53, 16, v22
	v_and_b32_e32 v22, 0xffff0000, v22
	v_lshlrev_b32_e32 v54, 16, v23
	v_and_b32_e32 v23, 0xffff0000, v23
	s_waitcnt vmcnt(9)
	v_lshlrev_b32_e32 v55, 16, v16
	v_and_b32_e32 v16, 0xffff0000, v16
	v_lshlrev_b32_e32 v56, 16, v17
	v_and_b32_e32 v17, 0xffff0000, v17
	v_lshlrev_b32_e32 v57, 16, v18
	v_and_b32_e32 v18, 0xffff0000, v18
	v_lshlrev_b32_e32 v58, 16, v19
	v_and_b32_e32 v19, 0xffff0000, v19
	s_waitcnt vmcnt(8)
	v_lshlrev_b32_e32 v59, 16, v12
	v_and_b32_e32 v12, 0xffff0000, v12
	v_lshlrev_b32_e32 v60, 16, v13
	v_and_b32_e32 v13, 0xffff0000, v13
	v_lshlrev_b32_e32 v61, 16, v14
	v_and_b32_e32 v14, 0xffff0000, v14
	v_lshlrev_b32_e32 v62, 16, v15
	v_and_b32_e32 v15, 0xffff0000, v15
	v_lshlrev_b32_e32 v63, 16, v8
	v_and_b32_e32 v64, 0xffff0000, v8
	v_lshlrev_b32_e32 v65, 16, v9
	v_and_b32_e32 v66, 0xffff0000, v9
	v_lshlrev_b32_e32 v67, 16, v10
	v_and_b32_e32 v68, 0xffff0000, v10
	v_lshlrev_b32_e32 v69, 16, v11
	v_and_b32_e32 v70, 0xffff0000, v11
	v_lshlrev_b32_e32 v71, 16, v4
	v_and_b32_e32 v72, 0xffff0000, v4
	v_lshlrev_b32_e32 v73, 16, v5
	v_and_b32_e32 v74, 0xffff0000, v5
	v_lshlrev_b32_e32 v4, 16, v6
	v_and_b32_e32 v5, 0xffff0000, v6
	v_lshlrev_b32_e32 v6, 16, v7
	v_and_b32_e32 v7, 0xffff0000, v7
	v_lshlrev_b32_e32 v8, 16, v0
	v_and_b32_e32 v9, 0xffff0000, v0
	v_lshlrev_b32_e32 v0, 16, v1
	v_and_b32_e32 v1, 0xffff0000, v1
	v_lshlrev_b32_e32 v10, 16, v2
	v_and_b32_e32 v11, 0xffff0000, v2
	v_lshlrev_b32_e32 v2, 16, v3
	v_and_b32_e32 v3, 0xffff0000, v3
	v_mov_b32_e32 v37, -1
	v_mov_b32_e32 v38, 0xff61b1e6
	s_mov_b64 s[40:41], 0
	v_mov_b32_e32 v76, 0xff61b1e6
	v_mov_b32_e32 v77, 0xff61b1e6
	v_mov_b32_e32 v79, -1
	v_mov_b32_e32 v78, -1
	v_mov_b32_e32 v75, v35
	s_branch .LBB0_419

; __device__ __forceinline__ void moba_unit(const Ctx& C, int unit, const float* KM) {
;     ...
;         for (int i = 0; i < 8; ++i) { const int d = tid + 512 * i; if (d < ndist) tabC[d] = tv[i]; }
; #pragma unroll
;         for (int i = 0; i < 2; ++i) { const int e = tid + 512 * i; if (e < qb * 64) kml[e] = kv[i] * (1.0f / 256.0f); }
.LBB0_424:
	s_waitcnt vmcnt(16)
	ds_write_b32 v46, v36 offset:10240
	s_or_b64 exec, exec, s[38:39]
	s_and_saveexec_b64 s[38:39], s[42:43]
	s_cbranch_execnz .LBB0_405

; __device__ __forceinline__ void moba_unit(const Ctx& C, int unit, const float* KM) {
;     ...
;         for (int i = 0; i < 8; ++i) { const int d = tid + 512 * i; if (d < ndist) tabC[d] = tv[i]; }
; #pragma unroll
;         for (int i = 0; i < 2; ++i) { const int e = tid + 512 * i; if (e < qb * 64) kml[e] = kv[i] * (1.0f / 256.0f); }
.LBB0_426:
	s_waitcnt vmcnt(16)
	ds_write_b32 v46, v35 offset:14336
	s_or_b64 exec, exec, s[38:39]
	s_and_saveexec_b64 s[38:39], s[46:47]
	s_cbranch_execnz .LBB0_407

; __device__ __forceinline__ void moba_unit(const Ctx& C, int unit, const float* KM) {
;     ...
;         for (int i = 0; i < 8; ++i) { const int d = tid + 512 * i; if (d < ndist) tabC[d] = tv[i]; }
; #pragma unroll
;         for (int i = 0; i < 2; ++i) { const int e = tid + 512 * i; if (e < qb * 64) kml[e] = kv[i] * (1.0f / 256.0f); }
.LBB0_428:
	s_waitcnt vmcnt(16)
	ds_write_b32 v46, v39 offset:18432
	s_or_b64 exec, exec, s[38:39]
	s_and_saveexec_b64 s[38:39], s[50:51]
	s_cbranch_execnz .LBB0_409

; __device__ __forceinline__ void moba_unit(const Ctx& C, int unit, const float* KM) {
;     ...
;         for (int i = 0; i < 8; ++i) { const int d = tid + 512 * i; if (d < ndist) tabC[d] = tv[i]; }
; #pragma unroll
;         for (int i = 0; i < 2; ++i) { const int e = tid + 512 * i; if (e < qb * 64) kml[e] = kv[i] * (1.0f / 256.0f); }
.LBB0_430:
	s_waitcnt vmcnt(16)
	ds_write_b32 v46, v41 offset:22528
	s_or_b64 exec, exec, s[38:39]
	s_and_saveexec_b64 s[38:39], s[54:55]
	s_cbranch_execnz .LBB0_411

; __device__ __forceinline__ void moba_unit(const Ctx& C, int unit, const float* KM) {
;     ...
;         for (int i = 0; i < 8; ++i) { const int d = tid + 512 * i; if (d < ndist) tabC[d] = tv[i]; }
; #pragma unroll
;         for (int i = 0; i < 2; ++i) { const int e = tid + 512 * i; if (e < qb * 64) kml[e] = kv[i] * (1.0f / 256.0f); }
.LBB0_432:
	s_waitcnt vmcnt(16)
	v_lshl_add_u32 v35, v42, 2, 0
	v_add_u32_e32 v35, 0x16000, v35
	v_mul_f32_e32 v44, 0x3b800000, v44
	ds_write_b32 v35, v44
	s_or_b64 exec, exec, s[38:39]
	v_cmp_gt_i32_e32 vcc, 16, v132
	s_and_saveexec_b64 s[38:39], vcc
	s_cbranch_execnz .LBB0_413
	s_branch .LBB0_414

; #define LAS __attribute__((address_space(3)))
; __device__ __forceinline__ void moba_unit(const Ctx& C, int unit, const float* KM) {
;     ...
;         LAS float* mg = (LAS float*)(lds + MB_K + 8192);
;         if (half == 1) { mg[qsel * 6 + 0] = v1; mg[qsel * 6 + 1] = v2; mg[qsel * 6 + 2] = v3;
;                          mg[qsel * 6 + 3] = __int_as_float(i1); mg[qsel * 6 + 4] = __int_as_float(i2); mg[qsel * 6 + 5] = __int_as_float(i3); }
;         __syncthreads();
;         if (half == 0) {
; #pragma unroll
;             for (int k = 0; k < 3; ++k) { const float s = mg[qsel * 6 + k]; const int n = __float_as_int(mg[qsel * 6 + 3 + k]);
;                 if (n >= 0) {
;                     if (s > v1 || (s == v1 && n < i1)) { v3 = v2; i3 = i2; v2 = v1; i2 = i1; v1 = s; i1 = n; }
;                     else if (s > v2 || (s == v2 && n < i2)) { v3 = v2; i3 = i2; v2 = s; i2 = n; }
;                     else if (s > v3 || (s == v3 && n < i3)) { v3 = s; i3 = n; } } }
;             if (i1 >= 0) { const int pos = __hip_atomic_fetch_add(cnt + i1, 1, __ATOMIC_RELAXED, __HIP_MEMORY_SCOPE_WORKGROUP); lists[i1 * 256 + pos] = (unsigned char)qsel; }
;             if (i2 >= 0) { const int pos = __hip_atomic_fetch_add(cnt + i2, 1, __ATOMIC_RELAXED, __HIP_MEMORY_SCOPE_WORKGROUP); lists[i2 * 256 + pos] = (unsigned char)qsel; }
;             if (i3 >= 0) { const int pos = __hip_atomic_fetch_add(cnt + i3, 1, __ATOMIC_RELAXED, __HIP_MEMORY_SCOPE_WORKGROUP); lists[i3 * 256 + pos] = (unsigned char)qsel; }
;         }
.LBB0_434:
	s_or_b64 exec, exec, s[38:39]
	v_cmp_eq_u32_e32 vcc, 1, v35
	s_and_saveexec_b64 s[38:39], vcc
	s_cbranch_execz .LBB0_436
	s_waitcnt vmcnt(12)
	v_mad_u32_u24 v0, v33, 24, 0
	v_add_u32_e32 v0, 0x18000, v0
	ds_write_b64 v0, v[40:41]
	ds_write2_b64 v0, v[38:39], v[36:37] offset0:1 offset1:2
.LBB0_436:
	s_or_b64 exec, exec, s[38:39]
	s_movk_i32 s20, 0x100
	v_cmp_gt_u32_e32 vcc, s20, v132
	s_waitcnt lgkmcnt(0)
	s_barrier
	s_and_saveexec_b64 s[40:41], vcc
	s_cbranch_execz .LBB0_485
	s_add_i32 s20, 0, 0x18000
	s_waitcnt vmcnt(12)
	v_mad_u32_u24 v1, v33, 24, s20
	ds_read_b32 v0, v1 offset:12
	s_waitcnt lgkmcnt(0)
	v_cmp_lt_i32_e32 vcc, -1, v0
	s_and_saveexec_b64 s[42:43], vcc
	s_cbranch_execz .LBB0_451
	ds_read_b32 v1, v1
	s_waitcnt lgkmcnt(0)
	v_cmp_ngt_f32_e32 vcc, v1, v40
	s_and_saveexec_b64 s[44:45], vcc
	s_cbranch_execz .LBB0_450
	v_cmp_neq_f32_e32 vcc, v1, v40
	v_cmp_ge_i32_e64 s[38:39], v0, v39
	s_or_b64 s[22:23], vcc, s[38:39]
	s_and_saveexec_b64 s[46:47], s[22:23]
	s_cbranch_execz .LBB0_449
	v_cmp_ngt_f32_e32 vcc, v1, v41
	s_and_saveexec_b64 s[48:49], vcc
	s_cbranch_execz .LBB0_448
	v_cmp_neq_f32_e32 vcc, v1, v41
	v_cmp_ge_i32_e64 s[38:39], v0, v36
	s_or_b64 s[22:23], vcc, s[38:39]
	s_and_saveexec_b64 s[50:51], s[22:23]
	s_cbranch_execz .LBB0_447
	v_cmp_gt_f32_e64 s[52:53], v1, v38
	v_cmp_ngt_f32_e32 vcc, v1, v38
	s_and_saveexec_b64 s[54:55], vcc
	v_cmp_eq_f32_e32 vcc, v1, v38
	v_cmp_lt_i32_e64 s[38:39], v0, v37
	s_and_b64 s[22:23], vcc, s[38:39]
	s_andn2_b64 s[24:25], s[52:53], exec
	s_and_b64 s[22:23], s[22:23], exec
	s_or_b64 s[52:53], s[24:25], s[22:23]
	s_or_b64 exec, exec, s[54:55]
	s_and_saveexec_b64 s[38:39], s[52:53]
	v_mov_b32_e32 v38, v1
	v_mov_b32_e32 v37, v0
	s_or_b64 exec, exec, s[38:39]
	v_mov_b32_e32 v1, v41
	v_mov_b32_e32 v41, v38
	v_mov_b32_e32 v0, v36
	v_mov_b32_e32 v36, v37

; #define MB_LOAD(nn) do { _Pragma("unroll") for (int i = 0; i < 4; ++i) { const int cidx = tid + 512 * i, row = cidx >> 3, ch = cidx & 7; \
;         const bf16* src = Zb + (size_t)((nn) * 256 + row) * ZC + h * 64 + ch * 8; kreg[i] = *(const v4u*)(src + KC); vreg[i] = *(const v4u*)(src + VC); } } while (0)
; __device__ __forceinline__ void moba_unit(const Ctx& C, int unit, const float* KM) {
;     ...
;     v4u kreg[4], vreg[4];
;     ...
;     MB_LOAD(qb);
;     __syncthreads();
.LBB0_485:
	s_or_b64 exec, exec, s[40:41]
	s_add_u32 s20, s66, s36
	s_waitcnt vmcnt(12)
	v_lshlrev_b32_e32 v0, 4, v132
	s_addc_u32 s21, s67, 0
	v_and_b32_e32 v192, 0x70, v0
	v_ashrrev_i32_e32 v188, 3, v132
	v_lshl_add_u64 v[104:105], s[20:21], 0, v[192:193]
	v_add_u32_e32 v0, s75, v188
	v_mad_i64_i32 v[0:1], s[20:21], v0, s33, v[104:105]
	s_movk_i32 s0, 0x1000
	v_add_co_u32_e32 v2, vcc, s0, v0
	v_ashrrev_i32_e32 v189, 3, v42
	s_nop 0
	v_addc_co_u32_e32 v3, vcc, 0, v1, vcc
	s_waitcnt vmcnt(11)
	v_add_co_u32_e32 v4, vcc, s5, v0
	s_waitcnt vmcnt(10)
	v_add_u32_e32 v8, s75, v189
	v_addc_co_u32_e32 v5, vcc, 0, v1, vcc
	v_mad_i64_i32 v[8:9], s[20:21], v8, s33, v[104:105]
	v_add_co_u32_e32 v10, vcc, s0, v8
	v_ashrrev_i32_e32 v190, 3, v32
	s_nop 0
	v_addc_co_u32_e32 v11, vcc, 0, v9, vcc
	s_waitcnt vmcnt(8)
	v_add_co_u32_e32 v12, vcc, s5, v8
	v_add_u32_e32 v16, s75, v190
	s_nop 0
	v_addc_co_u32_e32 v13, vcc, 0, v9, vcc
	v_mad_i64_i32 v[16:17], s[20:21], v16, s33, v[104:105]
	v_add_co_u32_e32 v18, vcc, s0, v16
	v_ashrrev_i32_e32 v191, 3, v34
	s_nop 0
	v_addc_co_u32_e32 v19, vcc, 0, v17, vcc
	v_add_co_u32_e32 v20, vcc, s5, v16
	v_add_u32_e32 v24, s75, v191
	s_nop 0
	v_addc_co_u32_e32 v21, vcc, 0, v17, vcc
	v_mad_i64_i32 v[24:25], s[20:21], v24, s33, v[104:105]
	v_add_co_u32_e32 v26, vcc, s0, v24
	s_nop 0
	v_addc_co_u32_e32 v27, vcc, 0, v25, vcc
	v_add_co_u32_e32 v28, vcc, s5, v24
	s_nop 0
	v_addc_co_u32_e32 v29, vcc, 0, v25, vcc
	s_nop 0
	s_nop 0
	s_nop 0
	s_add_i32 s20, 0, 0x16000
	v_lshlrev_b32_e32 v208, 2, v186
	v_bfe_u32 v35, v132, 2, 2
	v_and_b32_e32 v187, 15, v132
	v_lshrrev_b32_e32 v32, 1, v132
	v_mov_b32_e32 v33, s20
	s_movk_i32 s0, 0x90
	v_or_b32_e32 v35, v208, v35
	v_lshlrev_b32_e32 v36, 3, v169
	v_readlane_b32 s1, v248, 57
	v_and_b32_e32 v32, 24, v32
	v_mad_u32_u24 v33, v187, s0, v33
	v_and_b32_e32 v34, 48, v132
	v_mul_u32_u24_e32 v35, 0x90, v35
	v_and_b32_e32 v36, 24, v36
	s_mov_b32 s52, 0
	v_add_u32_e32 v206, s20, v192
	v_add_u32_e32 v207, s1, v192
	v_add3_u32 v209, s1, v35, v36
	v_or_b32_e32 v210, 4, v186
	v_or_b32_e32 v211, 8, v186
	v_or_b32_e32 v212, 12, v186
	v_cmp_gt_u32_e64 s[38:39], 16, v169
	v_or_b32_e32 v107, 3, v208
	v_or_b32_e32 v106, 2, v208
	v_or_b32_e32 v109, 17, v208
	v_or_b32_e32 v108, 16, v208
	v_or_b32_e32 v111, 19, v208
	v_or_b32_e32 v110, 18, v208
	v_or_b32_e32 v113, 33, v208
	v_or_b32_e32 v112, 32, v208
	v_or_b32_e32 v115, 35, v208
	v_or_b32_e32 v114, 34, v208
	v_or_b32_e32 v117, 49, v208
	v_or_b32_e32 v116, 48, v208
	v_or_b32_e32 v119, 51, v208
	v_or_b32_e32 v118, 50, v208
	v_or_b32_e32 v121, 0x41, v208
	v_or_b32_e32 v120, 64, v208
	v_or_b32_e32 v123, 0x43, v208
	v_or_b32_e32 v122, 0x42, v208
	v_or_b32_e32 v125, 0x51, v208
	v_or_b32_e32 v124, 0x50, v208
	v_or_b32_e32 v127, 0x53, v208
	v_or_b32_e32 v126, 0x52, v208
	v_or_b32_e32 v129, 0x61, v208
	v_or_b32_e32 v128, 0x60, v208
	v_or_b32_e32 v131, 0x63, v208
	v_or_b32_e32 v130, 0x62, v208
	v_or_b32_e32 v133, 0x71, v208
	v_or_b32_e32 v134, 0x70, v208
	v_or_b32_e32 v135, 0x73, v208
	v_or_b32_e32 v136, 0x72, v208
	v_or_b32_e32 v137, 0x81, v208
	v_or_b32_e32 v138, 0x80, v208
	v_or_b32_e32 v139, 0x83, v208
	v_or_b32_e32 v140, 0x82, v208
	v_or_b32_e32 v141, 0x91, v208
	v_or_b32_e32 v142, 0x90, v208
	v_or_b32_e32 v143, 0x93, v208
	v_or_b32_e32 v144, 0x92, v208
	v_or_b32_e32 v145, 0xa1, v208
	v_or_b32_e32 v146, 0xa0, v208
	v_or_b32_e32 v147, 0xa3, v208
	v_or_b32_e32 v148, 0xa2, v208
	v_or_b32_e32 v149, 0xb1, v208
	v_or_b32_e32 v150, 0xb0, v208
	v_or_b32_e32 v151, 0xb3, v208
	v_or_b32_e32 v152, 0xb2, v208
	v_or_b32_e32 v153, 0xc1, v208
	v_or_b32_e32 v154, 0xc0, v208
	v_or_b32_e32 v155, 0xc3, v208
	v_or_b32_e32 v156, 0xc2, v208
	v_or_b32_e32 v157, 0xd1, v208
	v_or_b32_e32 v158, 0xd0, v208
	v_or_b32_e32 v159, 0xd3, v208
	v_or_b32_e32 v160, 0xd2, v208
	v_or_b32_e32 v161, 0xe1, v208
	v_or_b32_e32 v162, 0xe0, v208
	v_or_b32_e32 v163, 0xe3, v208
	v_or_b32_e32 v164, 0xe2, v208
	v_or_b32_e32 v165, 0xf1, v208
	v_or_b32_e32 v166, 0xf0, v208
	v_or_b32_e32 v167, 0xf3, v208
	v_or_b32_e32 v168, 0xf2, v208
	s_sub_i32 s53, 16, s19
	v_mul_lo_u32 v213, v188, s0
	v_mul_lo_u32 v214, v189, s0
	v_mul_lo_u32 v215, v190, s0
	v_mul_lo_u32 v216, v191, s0
	s_sub_i32 s54, 15, s72
	v_lshl_or_b32 v217, s72, 4, v187
	v_lshlrev_b32_e32 v192, 1, v32
	v_add_u32_e32 v218, v33, v34
	s_waitcnt lgkmcnt(0)
	s_barrier
	s_branch .LBB0_487

; #define MB_STORE() do { _Pragma("unroll") for (int i = 0; i < 4; ++i) { const int cidx = tid + 512 * i, row = cidx >> 3, ch = cidx & 7; \
;         *(LAS v4u*)(lds + MB_K + row * 144 + ch * 16) = kreg[i]; *(LAS v4u*)(lds + MB_V + row * 144 + ch * 16) = vreg[i]; } } while (0)
; __device__ __forceinline__ void moba_unit(const Ctx& C, int unit, const float* KM) {
;     ...
;     for (int step = 0; step <= qb; ++step) {
;         __syncthreads();
;         MB_STORE();
;         __syncthreads();
.Lqp_step0:
	v_add_u32_e32 v32, v206, v213
	s_barrier
	s_waitcnt vmcnt(7)
	ds_write_b128 v32, v[170:173]
	v_add_u32_e32 v32, v207, v213
	s_waitcnt vmcnt(6)
	ds_write_b128 v32, v[174:177]
	v_add_u32_e32 v32, v206, v214
	s_waitcnt vmcnt(5)
	ds_write_b128 v32, v[178:181]
	v_add_u32_e32 v32, v207, v214
	s_waitcnt vmcnt(4)
	ds_write_b128 v32, v[182:185]
	v_add_u32_e32 v32, v206, v215
	s_waitcnt vmcnt(3)
	ds_write_b128 v32, v[222:225]
	v_add_u32_e32 v32, v207, v215
	s_waitcnt vmcnt(2)
	ds_write_b128 v32, v[238:241]
	v_add_u32_e32 v32, v206, v216
	s_waitcnt vmcnt(1)
	ds_write_b128 v32, v[242:245]
	v_add_u32_e32 v32, v207, v216
	s_cmp_ge_i32 s52, s70
	s_waitcnt vmcnt(0)
	ds_write_b128 v32, a[0:3]
	s_waitcnt lgkmcnt(0)
	s_barrier
